# stack: v18 edits + conv weight-load vmcnt(0) removed + LayerNorm 64-lane sums via DPP row ops/readlane instead of 12 serialized ds_bpermute round trips
# speedup vs baseline: 1.0005x; 1.0005x over previous
; DI float bflo(unsigned w) { return __uint_as_float(w << 16); }
; DI float bfhi(unsigned w) { return __uint_as_float(w & 0xffff0000u); }
; DI void phase_ln(const void* srcv, const int srcmode, const bf16_t* xres,
;                  const float* g, const float* b, float* dstf, bf16_t* dstb, int ntok, int tid,
;                  unsigned char* smem, const float* wg, const float* bias16, float* gpre) {
;     ...
;     for (int row = blockIdx.x * 8 + wid; row < ntok; row += rstride) {
;         f32x4 v[2][2]; float s = 0.f;
; #pragma unroll
;         for (int q = 0; q < 2; ++q) {
;             const u32x4 ra = na[q], rb = nb[q];
;             if (srcmode) {
;                 v[q][0] = (f32x4){bflo(ra.x) + ALPHA * bflo(rb.x), bfhi(ra.x) + ALPHA * bfhi(rb.x), bflo(ra.y) + ALPHA * bflo(rb.y), bfhi(ra.y) + ALPHA * bfhi(rb.y)};
;                 v[q][1] = (f32x4){bflo(ra.z) + ALPHA * bflo(rb.z), bfhi(ra.z) + ALPHA * bfhi(rb.z), bflo(ra.w) + ALPHA * bflo(rb.w), bfhi(ra.w) + ALPHA * bfhi(rb.w)};
;             } else { v[q][0] = __builtin_bit_cast(f32x4, ra); v[q][1] = __builtin_bit_cast(f32x4, rb); }
; #pragma unroll
;             for (int h = 0; h < 2; ++h) s += v[q][h][0] + v[q][h][1] + v[q][h][2] + v[q][h][3];
;         }
;         if (row + rstride < ntok) LN_LOAD(row + rstride);
; #pragma unroll
;         for (int o = 32; o >= 1; o >>= 1) s += __shfl_xor(s, o);
;         const float mu = s * (1.f / 1024.f);
;         float ss = 0.f;
; #pragma unroll
;         for (int q = 0; q < 2; ++q)
; #pragma unroll
;             for (int h = 0; h < 2; ++h) { v[q][h] = v[q][h] - mu; ss += v[q][h][0] * v[q][h][0] + v[q][h][1] * v[q][h][1] + v[q][h][2] * v[q][h][2] + v[q][h][3] * v[q][h][3]; }
; #pragma unroll
;         for (int o = 32; o >= 1; o >>= 1) ss += __shfl_xor(ss, o);
;         const float rstd = rsqrtf(ss * (1.f / 1024.f) + LN_EPS);
; #pragma unroll
;         for (int q = 0; q < 2; ++q) {
;             const f32x4 y0 = v[q][0] * rstd * gvv[q][0] + bvv[q][0], y1 = v[q][1] * rstd * gvv[q][1] + bvv[q][1];
;             if (dstf) { *(f32x4*)(dstf + (size_t)row * DM + q * 512 + lane * 8) = y0; *(f32x4*)(dstf + (size_t)row * DM + q * 512 + lane * 8 + 4) = y1; }
;             if (dstb) *(u32x4*)(dstb + (size_t)row * DM + q * 512 + lane * 8) = pack8(y0, y1);
;         }
;     }
.LBB0_89:
	s_or_b64 exec, exec, s[22:23]
	v_add_f32_e32 v77, v4, v5
	v_add_f32_e32 v77, v6, v77
	v_add_f32_e32 v78, v8, v9
	v_add_f32_e32 v77, v7, v77
	v_add_f32_e32 v78, v10, v78
	v_add_f32_e32 v77, 0, v77
	v_add_f32_e32 v78, v11, v78
	v_add_f32_e32 v77, v77, v78
	v_add_f32_e32 v78, v28, v29
	v_add_f32_e32 v78, v30, v78
	v_add_f32_e32 v78, v31, v78
	v_add_f32_e32 v77, v78, v77
	v_add_f32_e32 v78, v0, v1
	v_add_f32_e32 v78, v2, v78
	v_add_f32_e32 v78, v3, v78
	v_add_f32_e32 v77, v78, v77
	s_andn2_b64 vcc, exec, s[16:17]
	s_nop 0
	v_add_f32_dpp v77, v77, v77 quad_perm:[1,0,3,2] row_mask:0xf bank_mask:0xf
	s_nop 1
	v_add_f32_dpp v77, v77, v77 quad_perm:[2,3,0,1] row_mask:0xf bank_mask:0xf
	s_nop 1
	v_add_f32_dpp v77, v77, v77 row_half_mirror row_mask:0xf bank_mask:0xf
	s_nop 1
	v_add_f32_dpp v77, v77, v77 row_mirror row_mask:0xf bank_mask:0xf
	s_nop 0
	v_readlane_b32 s96, v77, 0
	v_readlane_b32 s97, v77, 16
	v_readlane_b32 s98, v77, 32
	v_readlane_b32 s99, v77, 48
	v_mov_b32_e32 v77, s96
	v_add_f32_e32 v77, s97, v77
	v_add_f32_e32 v77, s98, v77
	v_add_f32_e32 v77, s99, v77
	v_fmac_f32_e32 v5, 0xba800000, v77
	v_fmac_f32_e32 v9, 0xba800000, v77
	v_fmac_f32_e32 v4, 0xba800000, v77
	v_fmac_f32_e32 v8, 0xba800000, v77
	v_mul_f32_e32 v78, v5, v5
	v_mul_f32_e32 v79, v9, v9
	v_fmac_f32_e32 v6, 0xba800000, v77
	v_fmac_f32_e32 v10, 0xba800000, v77
	v_fmac_f32_e32 v78, v4, v4
	v_fmac_f32_e32 v79, v8, v8
	v_fmac_f32_e32 v7, 0xba800000, v77
	v_fmac_f32_e32 v11, 0xba800000, v77
	v_fmac_f32_e32 v78, v6, v6
	v_fmac_f32_e32 v79, v10, v10
	v_fmac_f32_e32 v29, 0xba800000, v77
	v_fmac_f32_e32 v78, v7, v7
	v_fmac_f32_e32 v79, v11, v11
	v_fmac_f32_e32 v28, 0xba800000, v77
	v_add_f32_e32 v78, v78, v79
	v_mul_f32_e32 v79, v29, v29
	v_fmac_f32_e32 v1, 0xba800000, v77
	v_fmac_f32_e32 v31, 0xba800000, v77
	v_fmac_f32_e32 v30, 0xba800000, v77
	v_fmac_f32_e32 v79, v28, v28
	v_fmac_f32_e32 v3, 0xba800000, v77
	v_fmac_f32_e32 v2, 0xba800000, v77
	v_fmac_f32_e32 v0, 0xba800000, v77
	v_mul_f32_e32 v77, v1, v1
	v_fmac_f32_e32 v79, v30, v30
	v_fmac_f32_e32 v77, v0, v0
	v_fmac_f32_e32 v79, v31, v31
	v_fmac_f32_e32 v77, v2, v2
	v_add_f32_e32 v78, v79, v78
	v_fmac_f32_e32 v77, v3, v3
	v_add_f32_e32 v77, v77, v78
	s_nop 1
	v_add_f32_dpp v77, v77, v77 quad_perm:[1,0,3,2] row_mask:0xf bank_mask:0xf
	s_nop 1
	v_add_f32_dpp v77, v77, v77 quad_perm:[2,3,0,1] row_mask:0xf bank_mask:0xf
	s_nop 1
	v_add_f32_dpp v77, v77, v77 row_half_mirror row_mask:0xf bank_mask:0xf
	s_nop 1
	v_add_f32_dpp v77, v77, v77 row_mirror row_mask:0xf bank_mask:0xf
	s_nop 0
	v_readlane_b32 s96, v77, 0
	v_readlane_b32 s97, v77, 16
	v_readlane_b32 s98, v77, 32
	v_readlane_b32 s99, v77, 48
	v_mov_b32_e32 v77, s96
	v_add_f32_e32 v77, s97, v77
	v_add_f32_e32 v77, s98, v77
	v_add_f32_e32 v77, s99, v77
	s_cbranch_vccnz .LBB0_86
	v_fmamk_f32 v77, v77, 0x3a800000, v65
	v_mul_f32_e32 v78, 0x4b800000, v77
	v_cmp_gt_f32_e32 vcc, s2, v77
	s_nop 1
	v_cndmask_b32_e32 v77, v77, v78, vcc
	v_rsq_f32_e32 v77, v77
	s_nop 0
	v_mul_f32_e32 v78, 0x45800000, v77
	v_cndmask_b32_e32 v78, v77, v78, vcc
	v_pk_mul_f32 v[8:9], v[8:9], v[78:79] op_sel_hi:[1,0]
	v_pk_mul_f32 v[10:11], v[10:11], v[78:79] op_sel_hi:[1,0]
	v_pk_mul_f32 v[4:5], v[4:5], v[78:79] op_sel_hi:[1,0]
	v_pk_mul_f32 v[6:7], v[6:7], v[78:79] op_sel_hi:[1,0]
	v_pk_fma_f32 v[10:11], v[14:15], v[10:11], v[18:19]
	v_pk_fma_f32 v[8:9], v[12:13], v[8:9], v[16:17]
	v_pk_fma_f32 v[6:7], v[22:23], v[6:7], v[26:27]
	v_pk_fma_f32 v[4:5], v[20:21], v[4:5], v[24:25]
	v_pk_mul_f32 v[0:1], v[0:1], v[78:79] op_sel_hi:[1,0]
	v_cvt_pk_bf16_f32 v4, v4, v5
	v_cvt_pk_bf16_f32 v5, v6, v7
	v_cvt_pk_bf16_f32 v6, v8, v9
	v_cvt_pk_bf16_f32 v7, v10, v11
	global_store_dwordx4 v[68:69], v[4:7], off offset:-1024
	v_pk_mul_f32 v[2:3], v[2:3], v[78:79] op_sel_hi:[1,0]
	s_nop 0
	v_pk_mul_f32 v[4:5], v[28:29], v[78:79] op_sel_hi:[1,0]
	v_pk_mul_f32 v[6:7], v[30:31], v[78:79] op_sel_hi:[1,0]
	s_waitcnt vmcnt(1)
	v_pk_fma_f32 v[4:5], v[40:41], v[4:5], v[44:45]
	v_pk_fma_f32 v[6:7], v[42:43], v[6:7], v[46:47]
	v_pk_fma_f32 v[8:9], v[34:35], v[2:3], v[38:39]
	v_pk_fma_f32 v[2:3], v[32:33], v[0:1], v[36:37]
	v_cvt_pk_bf16_f32 v0, v4, v5
	v_cvt_pk_bf16_f32 v1, v6, v7
	v_cvt_pk_bf16_f32 v2, v2, v3
	v_cvt_pk_bf16_f32 v3, v8, v9
	global_store_dwordx4 v[68:69], v[0:3], off
	s_branch .LBB0_86

; DI float bflo(unsigned w) { return __uint_as_float(w << 16); }
; DI float bfhi(unsigned w) { return __uint_as_float(w & 0xffff0000u); }
; DI void phase_ln(const void* srcv, const int srcmode, const bf16_t* xres,
;                  const float* g, const float* b, float* dstf, bf16_t* dstb, int ntok, int tid,
;                  unsigned char* smem, const float* wg, const float* bias16, float* gpre) {
;     ...
;     for (int row = blockIdx.x * 8 + wid; row < ntok; row += rstride) {
;         f32x4 v[2][2]; float s = 0.f;
; #pragma unroll
;         for (int q = 0; q < 2; ++q) {
;             const u32x4 ra = na[q], rb = nb[q];
;             if (srcmode) {
;                 v[q][0] = (f32x4){bflo(ra.x) + ALPHA * bflo(rb.x), bfhi(ra.x) + ALPHA * bfhi(rb.x), bflo(ra.y) + ALPHA * bflo(rb.y), bfhi(ra.y) + ALPHA * bfhi(rb.y)};
;                 v[q][1] = (f32x4){bflo(ra.z) + ALPHA * bflo(rb.z), bfhi(ra.z) + ALPHA * bfhi(rb.z), bflo(ra.w) + ALPHA * bflo(rb.w), bfhi(ra.w) + ALPHA * bfhi(rb.w)};
;             } else { v[q][0] = __builtin_bit_cast(f32x4, ra); v[q][1] = __builtin_bit_cast(f32x4, rb); }
; #pragma unroll
;             for (int h = 0; h < 2; ++h) s += v[q][h][0] + v[q][h][1] + v[q][h][2] + v[q][h][3];
;         }
;         if (row + rstride < ntok) LN_LOAD(row + rstride);
; #pragma unroll
;         for (int o = 32; o >= 1; o >>= 1) s += __shfl_xor(s, o);
;         const float mu = s * (1.f / 1024.f);
;         float ss = 0.f;
; #pragma unroll
;         for (int q = 0; q < 2; ++q)
; #pragma unroll
;             for (int h = 0; h < 2; ++h) { v[q][h] = v[q][h] - mu; ss += v[q][h][0] * v[q][h][0] + v[q][h][1] * v[q][h][1] + v[q][h][2] * v[q][h][2] + v[q][h][3] * v[q][h][3]; }
; #pragma unroll
;         for (int o = 32; o >= 1; o >>= 1) ss += __shfl_xor(ss, o);
;         const float rstd = rsqrtf(ss * (1.f / 1024.f) + LN_EPS);
; #pragma unroll
;         for (int q = 0; q < 2; ++q) {
;             const f32x4 y0 = v[q][0] * rstd * gvv[q][0] + bvv[q][0], y1 = v[q][1] * rstd * gvv[q][1] + bvv[q][1];
;             if (dstf) { *(f32x4*)(dstf + (size_t)row * DM + q * 512 + lane * 8) = y0; *(f32x4*)(dstf + (size_t)row * DM + q * 512 + lane * 8 + 4) = y1; }
.LBB0_180:
	s_or_b64 exec, exec, s[40:41]
	v_add_f32_e32 v59, v50, v51
	v_add_f32_e32 v59, v52, v59
	v_add_f32_e32 v81, v54, v55
	v_add_f32_e32 v59, v53, v59
	v_add_f32_e32 v81, v56, v81
	v_add_f32_e32 v59, 0, v59
	v_add_f32_e32 v81, v57, v81
	v_add_f32_e32 v59, v81, v59
	v_add_f32_e32 v81, v94, v95
	v_add_f32_e32 v81, v96, v81
	v_add_f32_e32 v81, v97, v81
	v_add_f32_e32 v59, v59, v81
	v_add_f32_e32 v81, v98, v99
	v_add_f32_e32 v81, v100, v81
	v_add_f32_e32 v81, v101, v81
	v_add_f32_e32 v59, v81, v59
	s_mov_b32 s13, 0x800000
	s_and_b64 s[30:31], exec, s[38:39]
	s_or_b64 s[50:51], s[30:31], s[50:51]
	v_add_f32_dpp v59, v59, v59 quad_perm:[1,0,3,2] row_mask:0xf bank_mask:0xf
	s_nop 1
	v_add_f32_dpp v59, v59, v59 quad_perm:[2,3,0,1] row_mask:0xf bank_mask:0xf
	s_nop 1
	v_add_f32_dpp v59, v59, v59 row_half_mirror row_mask:0xf bank_mask:0xf
	s_nop 1
	v_add_f32_dpp v59, v59, v59 row_mirror row_mask:0xf bank_mask:0xf
	s_nop 0
	v_readlane_b32 s96, v59, 0
	v_readlane_b32 s97, v59, 16
	v_readlane_b32 s98, v59, 32
	v_readlane_b32 s99, v59, 48
	v_mov_b32_e32 v59, s96
	v_add_f32_e32 v59, s97, v59
	v_add_f32_e32 v59, s98, v59
	v_add_f32_e32 v59, s99, v59
	v_fmac_f32_e32 v51, 0xba800000, v59
	v_fmac_f32_e32 v55, 0xba800000, v59
	v_fmac_f32_e32 v50, 0xba800000, v59
	v_fmac_f32_e32 v54, 0xba800000, v59
	v_mov_b32_e32 v104, v51
	v_mov_b32_e32 v105, v55
	v_fmac_f32_e32 v52, 0xba800000, v59
	v_fmac_f32_e32 v56, 0xba800000, v59
	v_mov_b32_e32 v102, v50
	v_mov_b32_e32 v103, v54
	v_pk_mul_f32 v[104:105], v[104:105], v[104:105]
	v_fmac_f32_e32 v53, 0xba800000, v59
	v_fmac_f32_e32 v57, 0xba800000, v59
	v_pk_fma_f32 v[102:103], v[102:103], v[102:103], v[104:105]
	v_mov_b32_e32 v104, v52
	v_mov_b32_e32 v105, v56
	v_fmac_f32_e32 v95, 0xba800000, v59
	v_fmac_f32_e32 v99, 0xba800000, v59
	v_pk_fma_f32 v[102:103], v[104:105], v[104:105], v[102:103]
	v_mov_b32_e32 v104, v53
	v_mov_b32_e32 v105, v57
	v_fmac_f32_e32 v94, 0xba800000, v59
	v_fmac_f32_e32 v98, 0xba800000, v59
	v_mov_b32_e32 v106, v99
	v_mov_b32_e32 v107, v95
	v_pk_fma_f32 v[102:103], v[104:105], v[104:105], v[102:103]
	v_fmac_f32_e32 v96, 0xba800000, v59
	v_fmac_f32_e32 v100, 0xba800000, v59
	v_mov_b32_e32 v104, v98
	v_mov_b32_e32 v105, v94
	v_pk_mul_f32 v[106:107], v[106:107], v[106:107]
	v_fmac_f32_e32 v97, 0xba800000, v59
	v_fmac_f32_e32 v101, 0xba800000, v59
	v_pk_fma_f32 v[104:105], v[104:105], v[104:105], v[106:107]
	v_mov_b32_e32 v106, v100
	v_mov_b32_e32 v107, v96
	v_pk_fma_f32 v[104:105], v[106:107], v[106:107], v[104:105]
	v_mov_b32_e32 v106, v101
	v_mov_b32_e32 v107, v97
	v_pk_fma_f32 v[104:105], v[106:107], v[106:107], v[104:105]
	v_add_f32_e32 v59, v102, v103
	v_add_f32_e32 v59, v105, v59
	v_add_f32_e32 v59, v104, v59
	v_lshl_add_u64 v[102:103], v[84:85], 0, v[72:73]
	s_nop 0
	v_add_f32_dpp v59, v59, v59 quad_perm:[1,0,3,2] row_mask:0xf bank_mask:0xf
	s_nop 1
	v_add_f32_dpp v59, v59, v59 quad_perm:[2,3,0,1] row_mask:0xf bank_mask:0xf
	s_nop 1
	v_add_f32_dpp v59, v59, v59 row_half_mirror row_mask:0xf bank_mask:0xf
	s_nop 1
	v_add_f32_dpp v59, v59, v59 row_mirror row_mask:0xf bank_mask:0xf
	s_nop 0
	v_readlane_b32 s96, v59, 0
	v_readlane_b32 s97, v59, 16
	v_readlane_b32 s98, v59, 32
	v_readlane_b32 s99, v59, 48
	v_mov_b32_e32 v59, s96
	v_add_f32_e32 v59, s97, v59
	v_add_f32_e32 v59, s98, v59
	v_add_f32_e32 v59, s99, v59
	v_fmamk_f32 v59, v59, 0x3a800000, v202
	v_cmp_gt_f32_e32 vcc, s13, v59
	v_mul_f32_e32 v81, 0x4b800000, v59
	s_nop 0
	v_cndmask_b32_e32 v59, v59, v81, vcc
	v_rsq_f32_e32 v59, v59
	s_nop 0
	v_mul_f32_e32 v81, 0x45800000, v59
	v_cndmask_b32_e32 v104, v59, v81, vcc
	v_pk_mul_f32 v[50:51], v[50:51], v[104:105] op_sel_hi:[1,0]
	v_pk_mul_f32 v[52:53], v[52:53], v[104:105] op_sel_hi:[1,0]
	v_pk_mul_f32 v[54:55], v[54:55], v[104:105] op_sel_hi:[1,0]
	v_pk_mul_f32 v[56:57], v[56:57], v[104:105] op_sel_hi:[1,0]
	v_cndmask_b32_e64 v59, 0, 1, s[52:53]
	s_waitcnt vmcnt(6)
	v_pk_fma_f32 v[52:53], v[8:9], v[52:53], v[16:17]
	v_pk_fma_f32 v[50:51], v[6:7], v[50:51], v[14:15]
	v_pk_fma_f32 v[56:57], v[4:5], v[56:57], v[12:13]
	v_pk_fma_f32 v[54:55], v[2:3], v[54:55], v[10:11]
	v_cmp_ne_u32_e64 s[38:39], 1, v59
	s_andn2_b64 vcc, exec, s[52:53]
	s_cbranch_vccnz .LBB0_182
	global_store_dwordx4 v[102:103], v[50:53], off
	global_store_dwordx4 v[102:103], v[54:57], off offset:16

; DI void phase_conv(const Params& p, int layer, int ntok, int S, int tid) {
;     ...
;     for (int task = blockIdx.x * 8 + wid; task < ntask; task += gridDim.x * 8) {
;         const int cwv = task % NCW, seg = task / NCW;
;         const int c = (cwv * 64 + lane) * 4;
;         const int t0 = seg * SEG, pos0 = t0 % S;
;         const f32x4 wv0 = *(const f32x4*)(cw + c), wv1 = *(const f32x4*)(cw + NUP + c), wv2 = *(const f32x4*)(cw + 2 * NUP + c), bv = *(const f32x4*)(cbias + c);
;         const f32x4 wg0 = *(const f32x4*)(cw + DFF + c), wg1 = *(const f32x4*)(cw + NUP + DFF + c), wg2 = *(const f32x4*)(cw + 2 * NUP + DFF + c), bg = *(const f32x4*)(cbias + DFF + c);
;         const bf16_t* hv = p.hu + (size_t)t0 * NUP + c; const bf16_t* hg = hv + DFF;
;         bf16_t* op = p.ff + (size_t)t0 * DFF + c;
;         const u32x2 z = {0u, 0u};
;         u32x2 rv[SEG + 2], rg[SEG + 2];
;         rv[0] = pos0 > 0 ? *(const u32x2*)(hv - NUP) : z; rg[0] = pos0 > 0 ? *(const u32x2*)(hg - NUP) : z;
; #pragma unroll
;         for (int i = 0; i < SEG; ++i) { rv[i + 1] = *(const u32x2*)(hv + (size_t)i * NUP); rg[i + 1] = *(const u32x2*)(hg + (size_t)i * NUP); }
;         { const bool hn = (pos0 + SEG - 1) < S - 1; rv[SEG + 1] = hn ? *(const u32x2*)(hv + (size_t)SEG * NUP) : z; rg[SEG + 1] = hn ? *(const u32x2*)(hg + (size_t)SEG * NUP) : z; }
.LBB0_219:
	s_mov_b32 s0, 0x2e8ba2e9
	v_mul_hi_i32 v2, v110, s0
	v_lshrrev_b32_e32 v3, 31, v2
	v_ashrrev_i32_e32 v2, 1, v2
	v_add_u32_e32 v34, v2, v3
	s_movk_i32 s0, 0xf500
	v_mad_u64_u32 v[36:37], s[0:1], v34, s0, v[0:1]
	v_ashrrev_i32_e32 v37, 31, v36
	v_lshlrev_b64 v[10:11], 2, v[36:37]
	v_lshl_add_u64 v[2:3], s[18:19], 0, v[10:11]
	v_lshl_add_u64 v[4:5], s[38:39], 0, v[10:11]
	global_load_dwordx4 v[26:29], v[2:3], off
	global_load_dwordx4 v[30:33], v[4:5], off
	v_lshl_add_u64 v[2:3], s[40:41], 0, v[10:11]
	global_load_dwordx4 v[18:21], v[2:3], off
	v_lshl_add_u64 v[2:3], s[36:37], 0, v[10:11]
	global_load_dwordx4 v[22:25], v[2:3], off
	v_lshl_add_u64 v[2:3], s[46:47], 0, v[10:11]
	v_lshl_add_u64 v[6:7], s[78:79], 0, v[10:11]
	global_load_dwordx4 v[2:5], v[2:3], off
	s_nop 0
	global_load_dwordx4 v[14:17], v[6:7], off
	v_lshl_add_u64 v[6:7], s[94:95], 0, v[10:11]
	v_lshl_add_u64 v[10:11], s[96:97], 0, v[10:11]
	global_load_dwordx4 v[6:9], v[6:7], off
	v_lshlrev_b32_e32 v112, 4, v34
	global_load_dwordx4 v[10:13], v[10:11], off
	v_sub_u32_e32 v38, 0, v112
	v_max_i32_e32 v38, v112, v38
	v_mul_hi_u32 v39, v38, v111
	v_mul_lo_u32 v39, v39, s23
	v_sub_u32_e32 v38, v38, v39
	v_subrev_u32_e32 v39, s23, v38
	v_cmp_le_u32_e32 vcc, s23, v38
	v_ashrrev_i32_e32 v35, 31, v112
	v_readlane_b32 s0, v255, 10
	v_cndmask_b32_e32 v38, v38, v39, vcc
	v_subrev_u32_e32 v39, s23, v38
	v_cmp_le_u32_e32 vcc, s23, v38
	v_readlane_b32 s1, v255, 11
	v_mov_b32_e32 v34, 0
	v_cndmask_b32_e32 v38, v38, v39, vcc
	v_xor_b32_e32 v38, v38, v35
	v_sub_u32_e32 v35, v38, v35
	v_mov_b64_e32 v[38:39], s[0:1]
	s_movk_i32 s0, 0x2c00
	v_mad_i64_i32 v[38:39], s[0:1], v112, s0, v[38:39]
	v_lshl_add_u64 v[100:101], v[36:37], 1, v[38:39]
	v_cmp_lt_i32_e32 vcc, 0, v35
	v_mov_b32_e32 v98, 0
	v_mov_b32_e32 v99, 0
	v_mov_b32_e32 v96, 0
	v_mov_b32_e32 v97, 0
	s_and_saveexec_b64 s[0:1], vcc
	s_cbranch_execz .LBB0_221
	v_add_co_u32_e32 v38, vcc, 0xffffe000, v100
	s_nop 1
	v_addc_co_u32_e32 v39, vcc, -1, v101, vcc
	v_add_co_u32_e32 v40, vcc, 0xfffff000, v100
	s_nop 1
	v_addc_co_u32_e32 v41, vcc, -1, v101, vcc
	global_load_dwordx2 v[98:99], v[38:39], off offset:-3072
	global_load_dwordx2 v[96:97], v[40:41], off offset:-1536

; DI float bflo(unsigned w) { return __uint_as_float(w << 16); }
; DI float bfhi(unsigned w) { return __uint_as_float(w & 0xffff0000u); }
; DI void phase_ln(const void* srcv, const int srcmode, const bf16_t* xres,
;                  const float* g, const float* b, float* dstf, bf16_t* dstb, int ntok, int tid,
;                  unsigned char* smem, const float* wg, const float* bias16, float* gpre) {
;     ...
;     for (int row = blockIdx.x * 8 + wid; row < ntok; row += rstride) {
;         f32x4 v[2][2]; float s = 0.f;
; #pragma unroll
;         for (int q = 0; q < 2; ++q) {
;             const u32x4 ra = na[q], rb = nb[q];
;             if (srcmode) {
;                 v[q][0] = (f32x4){bflo(ra.x) + ALPHA * bflo(rb.x), bfhi(ra.x) + ALPHA * bfhi(rb.x), bflo(ra.y) + ALPHA * bflo(rb.y), bfhi(ra.y) + ALPHA * bfhi(rb.y)};
;                 v[q][1] = (f32x4){bflo(ra.z) + ALPHA * bflo(rb.z), bfhi(ra.z) + ALPHA * bfhi(rb.z), bflo(ra.w) + ALPHA * bflo(rb.w), bfhi(ra.w) + ALPHA * bfhi(rb.w)};
;             } else { v[q][0] = __builtin_bit_cast(f32x4, ra); v[q][1] = __builtin_bit_cast(f32x4, rb); }
; #pragma unroll
;             for (int h = 0; h < 2; ++h) s += v[q][h][0] + v[q][h][1] + v[q][h][2] + v[q][h][3];
;         }
;         if (row + rstride < ntok) LN_LOAD(row + rstride);
; #pragma unroll
;         for (int o = 32; o >= 1; o >>= 1) s += __shfl_xor(s, o);
;         const float mu = s * (1.f / 1024.f);
;         float ss = 0.f;
; #pragma unroll
;         for (int q = 0; q < 2; ++q)
; #pragma unroll
;             for (int h = 0; h < 2; ++h) { v[q][h] = v[q][h] - mu; ss += v[q][h][0] * v[q][h][0] + v[q][h][1] * v[q][h][1] + v[q][h][2] * v[q][h][2] + v[q][h][3] * v[q][h][3]; }
; #pragma unroll
;         for (int o = 32; o >= 1; o >>= 1) ss += __shfl_xor(ss, o);
;         const float rstd = rsqrtf(ss * (1.f / 1024.f) + LN_EPS);
; #pragma unroll
;         for (int q = 0; q < 2; ++q) {
;             const f32x4 y0 = v[q][0] * rstd * gvv[q][0] + bvv[q][0], y1 = v[q][1] * rstd * gvv[q][1] + bvv[q][1];
;             if (dstf) { *(f32x4*)(dstf + (size_t)row * DM + q * 512 + lane * 8) = y0; *(f32x4*)(dstf + (size_t)row * DM + q * 512 + lane * 8 + 4) = y1; }
;             if (dstb) *(u32x4*)(dstb + (size_t)row * DM + q * 512 + lane * 8) = pack8(y0, y1);
;         }
;     }
.LBB0_254:
	s_or_b64 exec, exec, s[18:19]
	v_lshlrev_b32_e32 v74, 16, v62
	v_and_b32_e32 v75, 0xffff0000, v62
	v_lshlrev_b32_e32 v82, 16, v58
	v_and_b32_e32 v83, 0xffff0000, v58
	s_mov_b32 s2, 0x3fb504f3
	v_lshlrev_b32_e32 v62, 16, v63
	v_and_b32_e32 v63, 0xffff0000, v63
	v_lshlrev_b32_e32 v58, 16, v59
	v_and_b32_e32 v59, 0xffff0000, v59
	v_pk_fma_f32 v[74:75], v[82:83], s[2:3], v[74:75] op_sel_hi:[1,0,1]
	v_pk_fma_f32 v[58:59], v[58:59], s[2:3], v[62:63] op_sel_hi:[1,0,1]
	v_lshlrev_b32_e32 v62, 16, v64
	v_and_b32_e32 v63, 0xffff0000, v64
	v_lshlrev_b32_e32 v82, 16, v60
	v_and_b32_e32 v83, 0xffff0000, v60
	v_lshlrev_b32_e32 v64, 16, v65
	v_and_b32_e32 v65, 0xffff0000, v65
	v_lshlrev_b32_e32 v60, 16, v61
	v_and_b32_e32 v61, 0xffff0000, v61
	v_pk_fma_f32 v[62:63], v[82:83], s[2:3], v[62:63] op_sel_hi:[1,0,1]
	v_pk_fma_f32 v[64:65], v[60:61], s[2:3], v[64:65] op_sel_hi:[1,0,1]
	v_add_f32_e32 v60, v74, v75
	v_add_f32_e32 v60, v58, v60
	v_add_f32_e32 v61, v62, v63
	v_add_f32_e32 v60, v59, v60
	v_add_f32_e32 v61, v64, v61
	v_add_f32_e32 v60, 0, v60
	v_add_f32_e32 v61, v65, v61
	v_add_f32_e32 v81, v61, v60
	v_lshlrev_b32_e32 v60, 16, v54
	v_and_b32_e32 v61, 0xffff0000, v54
	v_lshlrev_b32_e32 v82, 16, v50
	v_and_b32_e32 v83, 0xffff0000, v50
	v_lshlrev_b32_e32 v54, 16, v55
	v_and_b32_e32 v55, 0xffff0000, v55
	v_lshlrev_b32_e32 v50, 16, v51
	v_and_b32_e32 v51, 0xffff0000, v51
	v_pk_fma_f32 v[60:61], v[82:83], s[2:3], v[60:61] op_sel_hi:[1,0,1]
	v_pk_fma_f32 v[50:51], v[50:51], s[2:3], v[54:55] op_sel_hi:[1,0,1]
	v_lshlrev_b32_e32 v54, 16, v56
	v_and_b32_e32 v55, 0xffff0000, v56
	v_lshlrev_b32_e32 v82, 16, v52
	v_and_b32_e32 v83, 0xffff0000, v52
	v_lshlrev_b32_e32 v56, 16, v57
	v_and_b32_e32 v57, 0xffff0000, v57
	v_lshlrev_b32_e32 v52, 16, v53
	v_and_b32_e32 v53, 0xffff0000, v53
	v_pk_fma_f32 v[54:55], v[82:83], s[2:3], v[54:55] op_sel_hi:[1,0,1]
	v_pk_fma_f32 v[52:53], v[52:53], s[2:3], v[56:57] op_sel_hi:[1,0,1]
	v_add_f32_e32 v56, v60, v61
	v_add_f32_e32 v56, v50, v56
	v_add_f32_e32 v57, v54, v55
	v_add_f32_e32 v56, v51, v56
	v_add_f32_e32 v57, v52, v57
	v_add_f32_e32 v56, v56, v81
	v_add_f32_e32 v57, v53, v57
	v_add_f32_e32 v56, v57, v56
	s_andn2_b64 vcc, exec, s[12:13]
	s_nop 0
	v_add_f32_dpp v56, v56, v56 quad_perm:[1,0,3,2] row_mask:0xf bank_mask:0xf
	s_nop 1
	v_add_f32_dpp v56, v56, v56 quad_perm:[2,3,0,1] row_mask:0xf bank_mask:0xf
	s_nop 1
	v_add_f32_dpp v56, v56, v56 row_half_mirror row_mask:0xf bank_mask:0xf
	s_nop 1
	v_add_f32_dpp v56, v56, v56 row_mirror row_mask:0xf bank_mask:0xf
	s_nop 0
	v_readlane_b32 s96, v56, 0
	v_readlane_b32 s97, v56, 16
	v_readlane_b32 s98, v56, 32
	v_readlane_b32 s99, v56, 48
	v_mov_b32_e32 v56, s96
	v_add_f32_e32 v56, s97, v56
	v_add_f32_e32 v56, s98, v56
	v_add_f32_e32 v56, s99, v56
	v_fmamk_f32 v75, v56, 0xba800000, v75
	v_fmamk_f32 v63, v56, 0xba800000, v63
	v_fmac_f32_e32 v74, 0xba800000, v56
	v_mul_f32_e32 v57, v75, v75
	v_fmac_f32_e32 v62, 0xba800000, v56
	v_mul_f32_e32 v81, v63, v63
	v_fmac_f32_e32 v58, 0xba800000, v56
	v_fmac_f32_e32 v57, v74, v74
	v_fmac_f32_e32 v64, 0xba800000, v56
	v_fmac_f32_e32 v81, v62, v62
	v_fmamk_f32 v59, v56, 0xba800000, v59
	v_fmac_f32_e32 v57, v58, v58
	v_fmamk_f32 v65, v56, 0xba800000, v65
	v_fmac_f32_e32 v81, v64, v64
	v_fmac_f32_e32 v57, v59, v59
	v_fmac_f32_e32 v81, v65, v65
	v_fmamk_f32 v61, v56, 0xba800000, v61
	v_add_f32_e32 v57, v57, v81
	v_fmac_f32_e32 v60, 0xba800000, v56
	v_mul_f32_e32 v81, v61, v61
	v_fmamk_f32 v55, v56, 0xba800000, v55
	v_fmamk_f32 v51, v56, 0xba800000, v51
	v_fmac_f32_e32 v50, 0xba800000, v56
	v_fmac_f32_e32 v81, v60, v60
	v_fmamk_f32 v53, v56, 0xba800000, v53
	v_fmac_f32_e32 v52, 0xba800000, v56
	v_fmac_f32_e32 v54, 0xba800000, v56
	v_mul_f32_e32 v56, v55, v55
	v_fmac_f32_e32 v81, v50, v50
	v_fmac_f32_e32 v56, v54, v54
	v_fmac_f32_e32 v81, v51, v51
	v_fmac_f32_e32 v56, v52, v52
	v_add_f32_e32 v57, v81, v57
	v_fmac_f32_e32 v56, v53, v53
	v_add_f32_e32 v56, v56, v57
	s_nop 1
	v_add_f32_dpp v56, v56, v56 quad_perm:[1,0,3,2] row_mask:0xf bank_mask:0xf
	s_nop 1
	v_add_f32_dpp v56, v56, v56 quad_perm:[2,3,0,1] row_mask:0xf bank_mask:0xf
	s_nop 1
	v_add_f32_dpp v56, v56, v56 row_half_mirror row_mask:0xf bank_mask:0xf
	s_nop 1
	v_add_f32_dpp v56, v56, v56 row_mirror row_mask:0xf bank_mask:0xf
	s_nop 0
	v_readlane_b32 s96, v56, 0
	v_readlane_b32 s97, v56, 16
	v_readlane_b32 s98, v56, 32
	v_readlane_b32 s99, v56, 48
	v_mov_b32_e32 v56, s96
	v_add_f32_e32 v56, s97, v56
	v_add_f32_e32 v56, s98, v56
	v_add_f32_e32 v56, s99, v56
	s_cbranch_vccnz .LBB0_251
	v_fmamk_f32 v56, v56, 0x3a800000, v202
	s_mov_b32 s2, 0x800000
	v_mul_f32_e32 v57, 0x4b800000, v56
	v_cmp_gt_f32_e32 vcc, s2, v56
	s_mov_b32 s2, 0x5110000
	s_nop 0
	v_cndmask_b32_e32 v56, v56, v57, vcc
	v_rsq_f32_e32 v56, v56
	s_nop 0
	v_mul_f32_e32 v57, 0x45800000, v56
	v_cndmask_b32_e32 v82, v56, v57, vcc
	v_pk_mul_f32 v[56:57], v[62:63], v[82:83] op_sel_hi:[1,0]
	v_pk_mul_f32 v[62:63], v[64:65], v[82:83] op_sel_hi:[1,0]
	v_pk_fma_f32 v[64:65], v[2:3], v[56:57], v[10:11]
	v_pk_mul_f32 v[56:57], v[74:75], v[82:83] op_sel_hi:[1,0]
	v_pk_mul_f32 v[58:59], v[58:59], v[82:83] op_sel_hi:[1,0]
	v_pk_fma_f32 v[62:63], v[4:5], v[62:63], v[12:13]
	v_pk_fma_f32 v[58:59], v[8:9], v[58:59], v[16:17]
	v_pk_fma_f32 v[56:57], v[6:7], v[56:57], v[14:15]
	v_lshl_add_u64 v[74:75], v[68:69], 0, v[0:1]
	v_cvt_pk_bf16_f32 v56, v56, v57
	v_cvt_pk_bf16_f32 v57, v58, v59
	v_cvt_pk_bf16_f32 v59, v62, v63
	v_add_co_u32_e32 v62, vcc, s2, v74
	v_cvt_pk_bf16_f32 v58, v64, v65
	s_nop 0
	v_addc_co_u32_e32 v63, vcc, 0, v75, vcc
	global_store_dwordx4 v[62:63], v[56:59], off
	v_pk_mul_f32 v[50:51], v[50:51], v[82:83] op_sel_hi:[1,0]
	v_pk_mul_f32 v[54:55], v[54:55], v[82:83] op_sel_hi:[1,0]
	v_pk_mul_f32 v[56:57], v[60:61], v[82:83] op_sel_hi:[1,0]
	v_pk_mul_f32 v[52:53], v[52:53], v[82:83] op_sel_hi:[1,0]
	v_pk_fma_f32 v[58:59], v[24:25], v[50:51], v[32:33]
	v_pk_fma_f32 v[50:51], v[22:23], v[56:57], v[30:31]
	v_pk_fma_f32 v[56:57], v[20:21], v[52:53], v[28:29]
	v_pk_fma_f32 v[52:53], v[18:19], v[54:55], v[26:27]
	v_cvt_pk_bf16_f32 v50, v50, v51
	v_cvt_pk_bf16_f32 v51, v58, v59
	v_cvt_pk_bf16_f32 v52, v52, v53
	v_cvt_pk_bf16_f32 v53, v56, v57
	global_store_dwordx4 v[62:63], v[50:53], off offset:1024
	s_branch .LBB0_251
